# SSD precompute: write-through (sc0 sc1) producer stores, no L2 flush
# speedup vs baseline: 1.0008x; 1.0008x over previous
; __device__ __forceinline__ unsigned cvt_pk(float lo, float hi) { f32x2 v = {lo, hi}; bf16x2_t b = __builtin_convertvector(v, bf16x2_t); return __builtin_bit_cast(unsigned, b); }
; __device__ __forceinline__ float bflo(unsigned w) { return __uint_as_float(w << 16); }
; __device__ __forceinline__ float bfhi(unsigned w) { return __uint_as_float(w & 0xffff0000u); }
; __device__ __forceinline__ float silu_f(float x) { return x * __builtin_amdgcn_rcpf(1.f + __builtin_amdgcn_exp2f(-1.4426950409f * x)); }
; __device__ __forceinline__ void ssd_prompt_item(const Params& p, int item, const int wv) {
;     ...
; #pragma unroll
;       for (int jj = 0; jj < 8; ++jj) {
;         float o[8];
; #pragma unroll
;         for (int e = 0; e < 8; ++e) o[e] = bias[e];
; #pragma unroll
;         for (int k = 0; k < 4; ++k) {
;           u32x4 uu = u[jj + k];
;           o[0] += w[k][0] * bflo(uu.x); o[1] += w[k][1] * bfhi(uu.x); o[2] += w[k][2] * bflo(uu.y); o[3] += w[k][3] * bfhi(uu.y);
;           o[4] += w[k][4] * bflo(uu.z); o[5] += w[k][5] * bfhi(uu.z); o[6] += w[k][6] * bflo(uu.w); o[7] += w[k][7] * bfhi(uu.w);
;         }
; #pragma unroll
;         for (int e = 0; e < 8; ++e) o[e] = silu_f(o[e]);
; #pragma unroll
;         for (int e2 = 0; e2 < 4; ++e2) outp[jj][e2] = cvt_pk(o[2 * e2], o[2 * e2 + 1]);
;       }
.Lssdp_nomask:
	v_lshlrev_b32_e32 v44, 16, v0
	v_and_b32_e32 v45, 0xffff0000, v0
	v_lshlrev_b32_e32 v46, 16, v1
	v_and_b32_e32 v47, 0xffff0000, v1
	v_lshlrev_b32_e32 v48, 16, v2
	v_and_b32_e32 v49, 0xffff0000, v2
	v_lshlrev_b32_e32 v50, 16, v3
	v_and_b32_e32 v51, 0xffff0000, v3
	v_lshlrev_b32_e32 v52, 16, v4
	v_and_b32_e32 v53, 0xffff0000, v4
	v_lshlrev_b32_e32 v54, 16, v5
	v_and_b32_e32 v55, 0xffff0000, v5
	v_lshlrev_b32_e32 v56, 16, v6
	v_and_b32_e32 v57, 0xffff0000, v6
	v_lshlrev_b32_e32 v58, 16, v7
	v_and_b32_e32 v59, 0xffff0000, v7
	v_lshlrev_b32_e32 v60, 16, v8
	v_and_b32_e32 v61, 0xffff0000, v8
	v_lshlrev_b32_e32 v62, 16, v9
	v_and_b32_e32 v63, 0xffff0000, v9
	v_lshlrev_b32_e32 v64, 16, v10
	v_and_b32_e32 v65, 0xffff0000, v10
	v_lshlrev_b32_e32 v66, 16, v11
	v_and_b32_e32 v67, 0xffff0000, v11
	v_lshlrev_b32_e32 v68, 16, v12
	v_and_b32_e32 v69, 0xffff0000, v12
	v_lshlrev_b32_e32 v70, 16, v13
	v_and_b32_e32 v71, 0xffff0000, v13
	v_lshlrev_b32_e32 v72, 16, v14
	v_and_b32_e32 v73, 0xffff0000, v14
	v_lshlrev_b32_e32 v74, 16, v15
	v_and_b32_e32 v75, 0xffff0000, v15
	v_lshlrev_b32_e32 v76, 16, v16
	v_and_b32_e32 v77, 0xffff0000, v16
	v_lshlrev_b32_e32 v78, 16, v17
	v_and_b32_e32 v79, 0xffff0000, v17
	v_lshlrev_b32_e32 v80, 16, v18
	v_and_b32_e32 v81, 0xffff0000, v18
	v_lshlrev_b32_e32 v82, 16, v19
	v_and_b32_e32 v83, 0xffff0000, v19
	v_lshlrev_b32_e32 v84, 16, v20
	v_and_b32_e32 v85, 0xffff0000, v20
	v_lshlrev_b32_e32 v86, 16, v21
	v_and_b32_e32 v87, 0xffff0000, v21
	v_lshlrev_b32_e32 v88, 16, v22
	v_and_b32_e32 v89, 0xffff0000, v22
	v_lshlrev_b32_e32 v90, 16, v23
	v_and_b32_e32 v91, 0xffff0000, v23
	v_lshlrev_b32_e32 v92, 16, v24
	v_and_b32_e32 v93, 0xffff0000, v24
	v_lshlrev_b32_e32 v94, 16, v25
	v_and_b32_e32 v95, 0xffff0000, v25
	v_lshlrev_b32_e32 v96, 16, v26
	v_and_b32_e32 v97, 0xffff0000, v26
	v_lshlrev_b32_e32 v98, 16, v27
	v_and_b32_e32 v99, 0xffff0000, v27
	v_lshlrev_b32_e32 v100, 16, v28
	v_and_b32_e32 v101, 0xffff0000, v28
	v_lshlrev_b32_e32 v102, 16, v29
	v_and_b32_e32 v103, 0xffff0000, v29
	v_lshlrev_b32_e32 v104, 16, v30
	v_and_b32_e32 v105, 0xffff0000, v30
	v_lshlrev_b32_e32 v106, 16, v31
	v_and_b32_e32 v107, 0xffff0000, v31
	v_lshlrev_b32_e32 v108, 16, v32
	v_and_b32_e32 v109, 0xffff0000, v32
	v_lshlrev_b32_e32 v110, 16, v33
	v_and_b32_e32 v111, 0xffff0000, v33
	v_lshlrev_b32_e32 v112, 16, v34
	v_and_b32_e32 v113, 0xffff0000, v34
	v_lshlrev_b32_e32 v114, 16, v35
	v_and_b32_e32 v115, 0xffff0000, v35
	v_lshlrev_b32_e32 v116, 16, v36
	v_and_b32_e32 v117, 0xffff0000, v36
	v_lshlrev_b32_e32 v118, 16, v37
	v_and_b32_e32 v119, 0xffff0000, v37
	v_lshlrev_b32_e32 v120, 16, v38
	v_and_b32_e32 v121, 0xffff0000, v38
	v_lshlrev_b32_e32 v122, 16, v39
	v_and_b32_e32 v123, 0xffff0000, v39
	v_lshlrev_b32_e32 v124, 16, v40
	v_and_b32_e32 v125, 0xffff0000, v40
	v_lshlrev_b32_e32 v126, 16, v41
	v_and_b32_e32 v127, 0xffff0000, v41
	v_lshlrev_b32_e32 v128, 16, v42
	v_and_b32_e32 v129, 0xffff0000, v42
	v_lshlrev_b32_e32 v130, 16, v43
	v_and_b32_e32 v131, 0xffff0000, v43
	v_pk_fma_f32 v[202:203], v[162:163], v[44:45], v[194:195]
	v_pk_fma_f32 v[204:205], v[164:165], v[46:47], v[196:197]
	v_pk_fma_f32 v[206:207], v[166:167], v[48:49], v[198:199]
	v_pk_fma_f32 v[208:209], v[168:169], v[50:51], v[200:201]
	v_pk_fma_f32 v[202:203], v[170:171], v[52:53], v[202:203]
	v_pk_fma_f32 v[204:205], v[172:173], v[54:55], v[204:205]
	v_pk_fma_f32 v[206:207], v[174:175], v[56:57], v[206:207]
	v_pk_fma_f32 v[208:209], v[176:177], v[58:59], v[208:209]
	v_pk_fma_f32 v[202:203], v[178:179], v[60:61], v[202:203]
	v_pk_fma_f32 v[204:205], v[180:181], v[62:63], v[204:205]
	v_pk_fma_f32 v[206:207], v[182:183], v[64:65], v[206:207]
	v_pk_fma_f32 v[208:209], v[184:185], v[66:67], v[208:209]
	v_pk_fma_f32 v[202:203], v[186:187], v[68:69], v[202:203]
	v_pk_fma_f32 v[204:205], v[188:189], v[70:71], v[204:205]
	v_pk_fma_f32 v[206:207], v[190:191], v[72:73], v[206:207]
	v_pk_fma_f32 v[208:209], v[192:193], v[74:75], v[208:209]
	v_mul_f32_e32 v210, 0xbfb8aa3b, v202
	v_mul_f32_e32 v211, 0xbfb8aa3b, v203
	v_mul_f32_e32 v212, 0xbfb8aa3b, v204
	v_mul_f32_e32 v213, 0xbfb8aa3b, v205
	v_mul_f32_e32 v214, 0xbfb8aa3b, v206
	v_mul_f32_e32 v215, 0xbfb8aa3b, v207
	v_mul_f32_e32 v216, 0xbfb8aa3b, v208
	v_mul_f32_e32 v217, 0xbfb8aa3b, v209
	v_exp_f32_e32 v210, v210
	v_exp_f32_e32 v211, v211
	v_exp_f32_e32 v212, v212
	v_exp_f32_e32 v213, v213
	v_exp_f32_e32 v214, v214
	v_exp_f32_e32 v215, v215
	v_exp_f32_e32 v216, v216
	v_exp_f32_e32 v217, v217
	v_add_f32_e32 v210, 1.0, v210
	v_add_f32_e32 v211, 1.0, v211
	v_add_f32_e32 v212, 1.0, v212
	v_add_f32_e32 v213, 1.0, v213
	v_add_f32_e32 v214, 1.0, v214
	v_add_f32_e32 v215, 1.0, v215
	v_add_f32_e32 v216, 1.0, v216
	v_add_f32_e32 v217, 1.0, v217
	v_rcp_f32_e32 v210, v210
	v_rcp_f32_e32 v211, v211
	v_rcp_f32_e32 v212, v212
	v_rcp_f32_e32 v213, v213
	v_rcp_f32_e32 v214, v214
	v_rcp_f32_e32 v215, v215
	v_rcp_f32_e32 v216, v216
	v_rcp_f32_e32 v217, v217
	v_pk_mul_f32 v[202:203], v[202:203], v[210:211]
	v_pk_mul_f32 v[204:205], v[204:205], v[212:213]
	v_pk_mul_f32 v[206:207], v[206:207], v[214:215]
	v_pk_mul_f32 v[208:209], v[208:209], v[216:217]
	v_cvt_pk_bf16_f32 v218, v202, v203
	v_cvt_pk_bf16_f32 v219, v204, v205
	v_cvt_pk_bf16_f32 v220, v206, v207
	v_cvt_pk_bf16_f32 v221, v208, v209
	global_store_dwordx4 v238, v[218:221], s[24:25] sc0 sc1
	v_pk_fma_f32 v[202:203], v[162:163], v[52:53], v[194:195]
	v_pk_fma_f32 v[204:205], v[164:165], v[54:55], v[196:197]
	v_pk_fma_f32 v[206:207], v[166:167], v[56:57], v[198:199]
	v_pk_fma_f32 v[208:209], v[168:169], v[58:59], v[200:201]
	v_pk_fma_f32 v[202:203], v[170:171], v[60:61], v[202:203]
; __device__ __forceinline__ unsigned cvt_pk(float lo, float hi) { f32x2 v = {lo, hi}; bf16x2_t b = __builtin_convertvector(v, bf16x2_t); return __builtin_bit_cast(unsigned, b); }
; __device__ __forceinline__ float bflo(unsigned w) { return __uint_as_float(w << 16); }
; __device__ __forceinline__ float bfhi(unsigned w) { return __uint_as_float(w & 0xffff0000u); }
; __device__ __forceinline__ float silu_f(float x) { return x * __builtin_amdgcn_rcpf(1.f + __builtin_amdgcn_exp2f(-1.4426950409f * x)); }
; __device__ __forceinline__ void ssd_prompt_item(const Params& p, int item, const int wv) {
;     ...
; #pragma unroll
;       for (int jj = 0; jj < 8; ++jj) {
;         float o[8];
; #pragma unroll
;         for (int e = 0; e < 8; ++e) o[e] = bias[e];
; #pragma unroll
;         for (int k = 0; k < 4; ++k) {
;           u32x4 uu = u[jj + k];
;           o[0] += w[k][0] * bflo(uu.x); o[1] += w[k][1] * bfhi(uu.x); o[2] += w[k][2] * bflo(uu.y); o[3] += w[k][3] * bfhi(uu.y);
;           o[4] += w[k][4] * bflo(uu.z); o[5] += w[k][5] * bfhi(uu.z); o[6] += w[k][6] * bflo(uu.w); o[7] += w[k][7] * bfhi(uu.w);
;         }
; #pragma unroll
;         for (int e = 0; e < 8; ++e) o[e] = silu_f(o[e]);
; #pragma unroll
;         for (int e2 = 0; e2 < 4; ++e2) outp[jj][e2] = cvt_pk(o[2 * e2], o[2 * e2 + 1]);
;       }
	v_pk_fma_f32 v[204:205], v[172:173], v[62:63], v[204:205]
	v_pk_fma_f32 v[206:207], v[174:175], v[64:65], v[206:207]
	v_pk_fma_f32 v[208:209], v[176:177], v[66:67], v[208:209]
	v_pk_fma_f32 v[202:203], v[178:179], v[68:69], v[202:203]
	v_pk_fma_f32 v[204:205], v[180:181], v[70:71], v[204:205]
	v_pk_fma_f32 v[206:207], v[182:183], v[72:73], v[206:207]
	v_pk_fma_f32 v[208:209], v[184:185], v[74:75], v[208:209]
	v_pk_fma_f32 v[202:203], v[186:187], v[76:77], v[202:203]
	v_pk_fma_f32 v[204:205], v[188:189], v[78:79], v[204:205]
	v_pk_fma_f32 v[206:207], v[190:191], v[80:81], v[206:207]
	v_pk_fma_f32 v[208:209], v[192:193], v[82:83], v[208:209]
	v_mul_f32_e32 v210, 0xbfb8aa3b, v202
	v_mul_f32_e32 v211, 0xbfb8aa3b, v203
	v_mul_f32_e32 v212, 0xbfb8aa3b, v204
	v_mul_f32_e32 v213, 0xbfb8aa3b, v205
	v_mul_f32_e32 v214, 0xbfb8aa3b, v206
	v_mul_f32_e32 v215, 0xbfb8aa3b, v207
	v_mul_f32_e32 v216, 0xbfb8aa3b, v208
	v_mul_f32_e32 v217, 0xbfb8aa3b, v209
	v_exp_f32_e32 v210, v210
	v_exp_f32_e32 v211, v211
	v_exp_f32_e32 v212, v212
	v_exp_f32_e32 v213, v213
	v_exp_f32_e32 v214, v214
	v_exp_f32_e32 v215, v215
	v_exp_f32_e32 v216, v216
	v_exp_f32_e32 v217, v217
	v_add_f32_e32 v210, 1.0, v210
	v_add_f32_e32 v211, 1.0, v211
	v_add_f32_e32 v212, 1.0, v212
	v_add_f32_e32 v213, 1.0, v213
	v_add_f32_e32 v214, 1.0, v214
	v_add_f32_e32 v215, 1.0, v215
	v_add_f32_e32 v216, 1.0, v216
	v_add_f32_e32 v217, 1.0, v217
	v_rcp_f32_e32 v210, v210
	v_rcp_f32_e32 v211, v211
	v_rcp_f32_e32 v212, v212
	v_rcp_f32_e32 v213, v213
	v_rcp_f32_e32 v214, v214
	v_rcp_f32_e32 v215, v215
	v_rcp_f32_e32 v216, v216
	v_rcp_f32_e32 v217, v217
	v_pk_mul_f32 v[202:203], v[202:203], v[210:211]
	v_pk_mul_f32 v[204:205], v[204:205], v[212:213]
	v_pk_mul_f32 v[206:207], v[206:207], v[214:215]
	v_pk_mul_f32 v[208:209], v[208:209], v[216:217]
	v_cvt_pk_bf16_f32 v222, v202, v203
	v_cvt_pk_bf16_f32 v223, v204, v205
	v_cvt_pk_bf16_f32 v224, v206, v207
	v_cvt_pk_bf16_f32 v225, v208, v209
	global_store_dwordx4 v238, v[222:225], s[24:25] offset:1024 sc0 sc1
	v_pk_fma_f32 v[202:203], v[162:163], v[60:61], v[194:195]
	v_pk_fma_f32 v[204:205], v[164:165], v[62:63], v[196:197]
	v_pk_fma_f32 v[206:207], v[166:167], v[64:65], v[198:199]
	v_pk_fma_f32 v[208:209], v[168:169], v[66:67], v[200:201]
	v_pk_fma_f32 v[202:203], v[170:171], v[68:69], v[202:203]
	v_pk_fma_f32 v[204:205], v[172:173], v[70:71], v[204:205]
	v_pk_fma_f32 v[206:207], v[174:175], v[72:73], v[206:207]
	v_pk_fma_f32 v[208:209], v[176:177], v[74:75], v[208:209]
	v_pk_fma_f32 v[202:203], v[178:179], v[76:77], v[202:203]
	v_pk_fma_f32 v[204:205], v[180:181], v[78:79], v[204:205]
	v_pk_fma_f32 v[206:207], v[182:183], v[80:81], v[206:207]
	v_pk_fma_f32 v[208:209], v[184:185], v[82:83], v[208:209]
	v_pk_fma_f32 v[202:203], v[186:187], v[84:85], v[202:203]
	v_pk_fma_f32 v[204:205], v[188:189], v[86:87], v[204:205]
	v_pk_fma_f32 v[206:207], v[190:191], v[88:89], v[206:207]
	v_pk_fma_f32 v[208:209], v[192:193], v[90:91], v[208:209]
	v_mul_f32_e32 v210, 0xbfb8aa3b, v202
	v_mul_f32_e32 v211, 0xbfb8aa3b, v203
	v_mul_f32_e32 v212, 0xbfb8aa3b, v204
	v_mul_f32_e32 v213, 0xbfb8aa3b, v205
	v_mul_f32_e32 v214, 0xbfb8aa3b, v206
	v_mul_f32_e32 v215, 0xbfb8aa3b, v207
	v_mul_f32_e32 v216, 0xbfb8aa3b, v208
	v_mul_f32_e32 v217, 0xbfb8aa3b, v209
	v_exp_f32_e32 v210, v210
	v_exp_f32_e32 v211, v211
	v_exp_f32_e32 v212, v212
	v_exp_f32_e32 v213, v213
	v_exp_f32_e32 v214, v214
	v_exp_f32_e32 v215, v215
	v_exp_f32_e32 v216, v216
	v_exp_f32_e32 v217, v217
	v_add_f32_e32 v210, 1.0, v210
	v_add_f32_e32 v211, 1.0, v211
	v_add_f32_e32 v212, 1.0, v212
	v_add_f32_e32 v213, 1.0, v213
	v_add_f32_e32 v214, 1.0, v214
	v_add_f32_e32 v215, 1.0, v215
	v_add_f32_e32 v216, 1.0, v216
	v_add_f32_e32 v217, 1.0, v217
	v_rcp_f32_e32 v210, v210
	v_rcp_f32_e32 v211, v211
	v_rcp_f32_e32 v212, v212
	v_rcp_f32_e32 v213, v213
	v_rcp_f32_e32 v214, v214
	v_rcp_f32_e32 v215, v215
	v_rcp_f32_e32 v216, v216
	v_rcp_f32_e32 v217, v217
	v_pk_mul_f32 v[202:203], v[202:203], v[210:211]
	v_pk_mul_f32 v[204:205], v[204:205], v[212:213]
	v_pk_mul_f32 v[206:207], v[206:207], v[214:215]
	v_pk_mul_f32 v[208:209], v[208:209], v[216:217]
	v_cvt_pk_bf16_f32 v218, v202, v203
	v_cvt_pk_bf16_f32 v219, v204, v205
	v_cvt_pk_bf16_f32 v220, v206, v207
	v_cvt_pk_bf16_f32 v221, v208, v209
	global_store_dwordx4 v238, v[218:221], s[24:25] offset:2048 sc0 sc1
	v_pk_fma_f32 v[202:203], v[162:163], v[68:69], v[194:195]
	v_pk_fma_f32 v[204:205], v[164:165], v[70:71], v[196:197]
	v_pk_fma_f32 v[206:207], v[166:167], v[72:73], v[198:199]
	v_pk_fma_f32 v[208:209], v[168:169], v[74:75], v[200:201]
	v_pk_fma_f32 v[202:203], v[170:171], v[76:77], v[202:203]
	v_pk_fma_f32 v[204:205], v[172:173], v[78:79], v[204:205]
	v_pk_fma_f32 v[206:207], v[174:175], v[80:81], v[206:207]
	v_pk_fma_f32 v[208:209], v[176:177], v[82:83], v[208:209]
	v_pk_fma_f32 v[202:203], v[178:179], v[84:85], v[202:203]
	v_pk_fma_f32 v[204:205], v[180:181], v[86:87], v[204:205]
	v_pk_fma_f32 v[206:207], v[182:183], v[88:89], v[206:207]
	v_pk_fma_f32 v[208:209], v[184:185], v[90:91], v[208:209]
	v_pk_fma_f32 v[202:203], v[186:187], v[92:93], v[202:203]
	v_pk_fma_f32 v[204:205], v[188:189], v[94:95], v[204:205]
	v_pk_fma_f32 v[206:207], v[190:191], v[96:97], v[206:207]
	v_pk_fma_f32 v[208:209], v[192:193], v[98:99], v[208:209]
	v_mul_f32_e32 v210, 0xbfb8aa3b, v202
	v_mul_f32_e32 v211, 0xbfb8aa3b, v203
	v_mul_f32_e32 v212, 0xbfb8aa3b, v204
	v_mul_f32_e32 v213, 0xbfb8aa3b, v205
	v_mul_f32_e32 v214, 0xbfb8aa3b, v206
	v_mul_f32_e32 v215, 0xbfb8aa3b, v207
	v_mul_f32_e32 v216, 0xbfb8aa3b, v208
	v_mul_f32_e32 v217, 0xbfb8aa3b, v209
	v_exp_f32_e32 v210, v210
	v_exp_f32_e32 v211, v211
; __device__ __forceinline__ unsigned cvt_pk(float lo, float hi) { f32x2 v = {lo, hi}; bf16x2_t b = __builtin_convertvector(v, bf16x2_t); return __builtin_bit_cast(unsigned, b); }
; __device__ __forceinline__ float bflo(unsigned w) { return __uint_as_float(w << 16); }
; __device__ __forceinline__ float bfhi(unsigned w) { return __uint_as_float(w & 0xffff0000u); }
; __device__ __forceinline__ float silu_f(float x) { return x * __builtin_amdgcn_rcpf(1.f + __builtin_amdgcn_exp2f(-1.4426950409f * x)); }
; __device__ __forceinline__ void ssd_prompt_item(const Params& p, int item, const int wv) {
;     ...
; #pragma unroll
;       for (int jj = 0; jj < 8; ++jj) {
;         float o[8];
; #pragma unroll
;         for (int e = 0; e < 8; ++e) o[e] = bias[e];
; #pragma unroll
;         for (int k = 0; k < 4; ++k) {
;           u32x4 uu = u[jj + k];
;           o[0] += w[k][0] * bflo(uu.x); o[1] += w[k][1] * bfhi(uu.x); o[2] += w[k][2] * bflo(uu.y); o[3] += w[k][3] * bfhi(uu.y);
;           o[4] += w[k][4] * bflo(uu.z); o[5] += w[k][5] * bfhi(uu.z); o[6] += w[k][6] * bflo(uu.w); o[7] += w[k][7] * bfhi(uu.w);
;         }
; #pragma unroll
;         for (int e = 0; e < 8; ++e) o[e] = silu_f(o[e]);
; #pragma unroll
;         for (int e2 = 0; e2 < 4; ++e2) outp[jj][e2] = cvt_pk(o[2 * e2], o[2 * e2 + 1]);
;       }
	v_exp_f32_e32 v212, v212
	v_exp_f32_e32 v213, v213
	v_exp_f32_e32 v214, v214
	v_exp_f32_e32 v215, v215
	v_exp_f32_e32 v216, v216
	v_exp_f32_e32 v217, v217
	v_add_f32_e32 v210, 1.0, v210
	v_add_f32_e32 v211, 1.0, v211
	v_add_f32_e32 v212, 1.0, v212
	v_add_f32_e32 v213, 1.0, v213
	v_add_f32_e32 v214, 1.0, v214
	v_add_f32_e32 v215, 1.0, v215
	v_add_f32_e32 v216, 1.0, v216
	v_add_f32_e32 v217, 1.0, v217
	v_rcp_f32_e32 v210, v210
	v_rcp_f32_e32 v211, v211
	v_rcp_f32_e32 v212, v212
	v_rcp_f32_e32 v213, v213
	v_rcp_f32_e32 v214, v214
	v_rcp_f32_e32 v215, v215
	v_rcp_f32_e32 v216, v216
	v_rcp_f32_e32 v217, v217
	v_pk_mul_f32 v[202:203], v[202:203], v[210:211]
	v_pk_mul_f32 v[204:205], v[204:205], v[212:213]
	v_pk_mul_f32 v[206:207], v[206:207], v[214:215]
	v_pk_mul_f32 v[208:209], v[208:209], v[216:217]
	v_cvt_pk_bf16_f32 v222, v202, v203
	v_cvt_pk_bf16_f32 v223, v204, v205
	v_cvt_pk_bf16_f32 v224, v206, v207
	v_cvt_pk_bf16_f32 v225, v208, v209
	global_store_dwordx4 v238, v[222:225], s[24:25] offset:3072 sc0 sc1
	v_pk_fma_f32 v[202:203], v[162:163], v[76:77], v[194:195]
	v_pk_fma_f32 v[204:205], v[164:165], v[78:79], v[196:197]
	v_pk_fma_f32 v[206:207], v[166:167], v[80:81], v[198:199]
	v_pk_fma_f32 v[208:209], v[168:169], v[82:83], v[200:201]
	v_pk_fma_f32 v[202:203], v[170:171], v[84:85], v[202:203]
	v_pk_fma_f32 v[204:205], v[172:173], v[86:87], v[204:205]
	v_pk_fma_f32 v[206:207], v[174:175], v[88:89], v[206:207]
	v_pk_fma_f32 v[208:209], v[176:177], v[90:91], v[208:209]
	v_pk_fma_f32 v[202:203], v[178:179], v[92:93], v[202:203]
	v_pk_fma_f32 v[204:205], v[180:181], v[94:95], v[204:205]
	v_pk_fma_f32 v[206:207], v[182:183], v[96:97], v[206:207]
	v_pk_fma_f32 v[208:209], v[184:185], v[98:99], v[208:209]
	v_pk_fma_f32 v[202:203], v[186:187], v[100:101], v[202:203]
	v_pk_fma_f32 v[204:205], v[188:189], v[102:103], v[204:205]
	v_pk_fma_f32 v[206:207], v[190:191], v[104:105], v[206:207]
	v_pk_fma_f32 v[208:209], v[192:193], v[106:107], v[208:209]
	v_mul_f32_e32 v210, 0xbfb8aa3b, v202
	v_mul_f32_e32 v211, 0xbfb8aa3b, v203
	v_mul_f32_e32 v212, 0xbfb8aa3b, v204
	v_mul_f32_e32 v213, 0xbfb8aa3b, v205
	v_mul_f32_e32 v214, 0xbfb8aa3b, v206
	v_mul_f32_e32 v215, 0xbfb8aa3b, v207
	v_mul_f32_e32 v216, 0xbfb8aa3b, v208
	v_mul_f32_e32 v217, 0xbfb8aa3b, v209
	v_exp_f32_e32 v210, v210
	v_exp_f32_e32 v211, v211
	v_exp_f32_e32 v212, v212
	v_exp_f32_e32 v213, v213
	v_exp_f32_e32 v214, v214
	v_exp_f32_e32 v215, v215
	v_exp_f32_e32 v216, v216
	v_exp_f32_e32 v217, v217
	v_add_f32_e32 v210, 1.0, v210
	v_add_f32_e32 v211, 1.0, v211
	v_add_f32_e32 v212, 1.0, v212
	v_add_f32_e32 v213, 1.0, v213
	v_add_f32_e32 v214, 1.0, v214
	v_add_f32_e32 v215, 1.0, v215
	v_add_f32_e32 v216, 1.0, v216
	v_add_f32_e32 v217, 1.0, v217
	v_rcp_f32_e32 v210, v210
	v_rcp_f32_e32 v211, v211
	v_rcp_f32_e32 v212, v212
	v_rcp_f32_e32 v213, v213
	v_rcp_f32_e32 v214, v214
	v_rcp_f32_e32 v215, v215
	v_rcp_f32_e32 v216, v216
	v_rcp_f32_e32 v217, v217
	v_pk_mul_f32 v[202:203], v[202:203], v[210:211]
	v_pk_mul_f32 v[204:205], v[204:205], v[212:213]
	v_pk_mul_f32 v[206:207], v[206:207], v[214:215]
	v_pk_mul_f32 v[208:209], v[208:209], v[216:217]
	v_cvt_pk_bf16_f32 v218, v202, v203
	v_cvt_pk_bf16_f32 v219, v204, v205
	v_cvt_pk_bf16_f32 v220, v206, v207
	v_cvt_pk_bf16_f32 v221, v208, v209
	global_store_dwordx4 v239, v[218:221], s[24:25] sc0 sc1
	v_pk_fma_f32 v[202:203], v[162:163], v[84:85], v[194:195]
	v_pk_fma_f32 v[204:205], v[164:165], v[86:87], v[196:197]
	v_pk_fma_f32 v[206:207], v[166:167], v[88:89], v[198:199]
	v_pk_fma_f32 v[208:209], v[168:169], v[90:91], v[200:201]
	v_pk_fma_f32 v[202:203], v[170:171], v[92:93], v[202:203]
	v_pk_fma_f32 v[204:205], v[172:173], v[94:95], v[204:205]
	v_pk_fma_f32 v[206:207], v[174:175], v[96:97], v[206:207]
	v_pk_fma_f32 v[208:209], v[176:177], v[98:99], v[208:209]
	v_pk_fma_f32 v[202:203], v[178:179], v[100:101], v[202:203]
	v_pk_fma_f32 v[204:205], v[180:181], v[102:103], v[204:205]
	v_pk_fma_f32 v[206:207], v[182:183], v[104:105], v[206:207]
	v_pk_fma_f32 v[208:209], v[184:185], v[106:107], v[208:209]
	v_pk_fma_f32 v[202:203], v[186:187], v[108:109], v[202:203]
	v_pk_fma_f32 v[204:205], v[188:189], v[110:111], v[204:205]
	v_pk_fma_f32 v[206:207], v[190:191], v[112:113], v[206:207]
	v_pk_fma_f32 v[208:209], v[192:193], v[114:115], v[208:209]
	v_mul_f32_e32 v210, 0xbfb8aa3b, v202
	v_mul_f32_e32 v211, 0xbfb8aa3b, v203
	v_mul_f32_e32 v212, 0xbfb8aa3b, v204
	v_mul_f32_e32 v213, 0xbfb8aa3b, v205
	v_mul_f32_e32 v214, 0xbfb8aa3b, v206
	v_mul_f32_e32 v215, 0xbfb8aa3b, v207
	v_mul_f32_e32 v216, 0xbfb8aa3b, v208
	v_mul_f32_e32 v217, 0xbfb8aa3b, v209
	v_exp_f32_e32 v210, v210
	v_exp_f32_e32 v211, v211
	v_exp_f32_e32 v212, v212
	v_exp_f32_e32 v213, v213
	v_exp_f32_e32 v214, v214
	v_exp_f32_e32 v215, v215
	v_exp_f32_e32 v216, v216
	v_exp_f32_e32 v217, v217
	v_add_f32_e32 v210, 1.0, v210
	v_add_f32_e32 v211, 1.0, v211
	v_add_f32_e32 v212, 1.0, v212
	v_add_f32_e32 v213, 1.0, v213
	v_add_f32_e32 v214, 1.0, v214
	v_add_f32_e32 v215, 1.0, v215
	v_add_f32_e32 v216, 1.0, v216
	v_add_f32_e32 v217, 1.0, v217
	v_rcp_f32_e32 v210, v210
	v_rcp_f32_e32 v211, v211
	v_rcp_f32_e32 v212, v212
	v_rcp_f32_e32 v213, v213
	v_rcp_f32_e32 v214, v214
	v_rcp_f32_e32 v215, v215
	v_rcp_f32_e32 v216, v216
	v_rcp_f32_e32 v217, v217
	v_pk_mul_f32 v[202:203], v[202:203], v[210:211]
	v_pk_mul_f32 v[204:205], v[204:205], v[212:213]
	v_pk_mul_f32 v[206:207], v[206:207], v[214:215]
; __device__ __forceinline__ unsigned cvt_pk(float lo, float hi) { f32x2 v = {lo, hi}; bf16x2_t b = __builtin_convertvector(v, bf16x2_t); return __builtin_bit_cast(unsigned, b); }
; __device__ __forceinline__ float bflo(unsigned w) { return __uint_as_float(w << 16); }
; __device__ __forceinline__ float bfhi(unsigned w) { return __uint_as_float(w & 0xffff0000u); }
; __device__ __forceinline__ float silu_f(float x) { return x * __builtin_amdgcn_rcpf(1.f + __builtin_amdgcn_exp2f(-1.4426950409f * x)); }
; __device__ __forceinline__ void ssd_prompt_item(const Params& p, int item, const int wv) {
;     ...
; #pragma unroll
;       for (int jj = 0; jj < 8; ++jj) {
;         float o[8];
; #pragma unroll
;         for (int e = 0; e < 8; ++e) o[e] = bias[e];
; #pragma unroll
;         for (int k = 0; k < 4; ++k) {
;           u32x4 uu = u[jj + k];
;           o[0] += w[k][0] * bflo(uu.x); o[1] += w[k][1] * bfhi(uu.x); o[2] += w[k][2] * bflo(uu.y); o[3] += w[k][3] * bfhi(uu.y);
;           o[4] += w[k][4] * bflo(uu.z); o[5] += w[k][5] * bfhi(uu.z); o[6] += w[k][6] * bflo(uu.w); o[7] += w[k][7] * bfhi(uu.w);
;         }
; #pragma unroll
;         for (int e = 0; e < 8; ++e) o[e] = silu_f(o[e]);
; #pragma unroll
;         for (int e2 = 0; e2 < 4; ++e2) outp[jj][e2] = cvt_pk(o[2 * e2], o[2 * e2 + 1]);
;       }
	v_pk_mul_f32 v[208:209], v[208:209], v[216:217]
	v_cvt_pk_bf16_f32 v222, v202, v203
	v_cvt_pk_bf16_f32 v223, v204, v205
	v_cvt_pk_bf16_f32 v224, v206, v207
	v_cvt_pk_bf16_f32 v225, v208, v209
	global_store_dwordx4 v239, v[222:225], s[24:25] offset:1024 sc0 sc1
	v_pk_fma_f32 v[202:203], v[162:163], v[92:93], v[194:195]
	v_pk_fma_f32 v[204:205], v[164:165], v[94:95], v[196:197]
	v_pk_fma_f32 v[206:207], v[166:167], v[96:97], v[198:199]
	v_pk_fma_f32 v[208:209], v[168:169], v[98:99], v[200:201]
	v_pk_fma_f32 v[202:203], v[170:171], v[100:101], v[202:203]
	v_pk_fma_f32 v[204:205], v[172:173], v[102:103], v[204:205]
	v_pk_fma_f32 v[206:207], v[174:175], v[104:105], v[206:207]
	v_pk_fma_f32 v[208:209], v[176:177], v[106:107], v[208:209]
	v_pk_fma_f32 v[202:203], v[178:179], v[108:109], v[202:203]
	v_pk_fma_f32 v[204:205], v[180:181], v[110:111], v[204:205]
	v_pk_fma_f32 v[206:207], v[182:183], v[112:113], v[206:207]
	v_pk_fma_f32 v[208:209], v[184:185], v[114:115], v[208:209]
	v_pk_fma_f32 v[202:203], v[186:187], v[116:117], v[202:203]
	v_pk_fma_f32 v[204:205], v[188:189], v[118:119], v[204:205]
	v_pk_fma_f32 v[206:207], v[190:191], v[120:121], v[206:207]
	v_pk_fma_f32 v[208:209], v[192:193], v[122:123], v[208:209]
	v_mul_f32_e32 v210, 0xbfb8aa3b, v202
	v_mul_f32_e32 v211, 0xbfb8aa3b, v203
	v_mul_f32_e32 v212, 0xbfb8aa3b, v204
	v_mul_f32_e32 v213, 0xbfb8aa3b, v205
	v_mul_f32_e32 v214, 0xbfb8aa3b, v206
	v_mul_f32_e32 v215, 0xbfb8aa3b, v207
	v_mul_f32_e32 v216, 0xbfb8aa3b, v208
	v_mul_f32_e32 v217, 0xbfb8aa3b, v209
	v_exp_f32_e32 v210, v210
	v_exp_f32_e32 v211, v211
	v_exp_f32_e32 v212, v212
	v_exp_f32_e32 v213, v213
	v_exp_f32_e32 v214, v214
	v_exp_f32_e32 v215, v215
	v_exp_f32_e32 v216, v216
	v_exp_f32_e32 v217, v217
	v_add_f32_e32 v210, 1.0, v210
	v_add_f32_e32 v211, 1.0, v211
	v_add_f32_e32 v212, 1.0, v212
	v_add_f32_e32 v213, 1.0, v213
	v_add_f32_e32 v214, 1.0, v214
	v_add_f32_e32 v215, 1.0, v215
	v_add_f32_e32 v216, 1.0, v216
	v_add_f32_e32 v217, 1.0, v217
	v_rcp_f32_e32 v210, v210
	v_rcp_f32_e32 v211, v211
	v_rcp_f32_e32 v212, v212
	v_rcp_f32_e32 v213, v213
	v_rcp_f32_e32 v214, v214
	v_rcp_f32_e32 v215, v215
	v_rcp_f32_e32 v216, v216
	v_rcp_f32_e32 v217, v217
	v_pk_mul_f32 v[202:203], v[202:203], v[210:211]
	v_pk_mul_f32 v[204:205], v[204:205], v[212:213]
	v_pk_mul_f32 v[206:207], v[206:207], v[214:215]
	v_pk_mul_f32 v[208:209], v[208:209], v[216:217]
	v_cvt_pk_bf16_f32 v218, v202, v203
	v_cvt_pk_bf16_f32 v219, v204, v205
	v_cvt_pk_bf16_f32 v220, v206, v207
	v_cvt_pk_bf16_f32 v221, v208, v209
	global_store_dwordx4 v239, v[218:221], s[24:25] offset:2048 sc0 sc1
	v_pk_fma_f32 v[202:203], v[162:163], v[100:101], v[194:195]
	v_pk_fma_f32 v[204:205], v[164:165], v[102:103], v[196:197]
	v_pk_fma_f32 v[206:207], v[166:167], v[104:105], v[198:199]
	v_pk_fma_f32 v[208:209], v[168:169], v[106:107], v[200:201]
	v_pk_fma_f32 v[202:203], v[170:171], v[108:109], v[202:203]
	v_pk_fma_f32 v[204:205], v[172:173], v[110:111], v[204:205]
	v_pk_fma_f32 v[206:207], v[174:175], v[112:113], v[206:207]
	v_pk_fma_f32 v[208:209], v[176:177], v[114:115], v[208:209]
	v_pk_fma_f32 v[202:203], v[178:179], v[116:117], v[202:203]
	v_pk_fma_f32 v[204:205], v[180:181], v[118:119], v[204:205]
	v_pk_fma_f32 v[206:207], v[182:183], v[120:121], v[206:207]
	v_pk_fma_f32 v[208:209], v[184:185], v[122:123], v[208:209]
	v_pk_fma_f32 v[202:203], v[186:187], v[124:125], v[202:203]
	v_pk_fma_f32 v[204:205], v[188:189], v[126:127], v[204:205]
	v_pk_fma_f32 v[206:207], v[190:191], v[128:129], v[206:207]
	v_pk_fma_f32 v[208:209], v[192:193], v[130:131], v[208:209]
	v_mul_f32_e32 v210, 0xbfb8aa3b, v202
	v_mul_f32_e32 v211, 0xbfb8aa3b, v203
	v_mul_f32_e32 v212, 0xbfb8aa3b, v204
	v_mul_f32_e32 v213, 0xbfb8aa3b, v205
	v_mul_f32_e32 v214, 0xbfb8aa3b, v206
	v_mul_f32_e32 v215, 0xbfb8aa3b, v207
	v_mul_f32_e32 v216, 0xbfb8aa3b, v208
	v_mul_f32_e32 v217, 0xbfb8aa3b, v209
	v_exp_f32_e32 v210, v210
	v_exp_f32_e32 v211, v211
	v_exp_f32_e32 v212, v212
	v_exp_f32_e32 v213, v213
	v_exp_f32_e32 v214, v214
	v_exp_f32_e32 v215, v215
	v_exp_f32_e32 v216, v216
	v_exp_f32_e32 v217, v217
	v_add_f32_e32 v210, 1.0, v210
	v_add_f32_e32 v211, 1.0, v211
	v_add_f32_e32 v212, 1.0, v212
	v_add_f32_e32 v213, 1.0, v213
	v_add_f32_e32 v214, 1.0, v214
	v_add_f32_e32 v215, 1.0, v215
	v_add_f32_e32 v216, 1.0, v216
	v_add_f32_e32 v217, 1.0, v217
	v_rcp_f32_e32 v210, v210
	v_rcp_f32_e32 v211, v211
	v_rcp_f32_e32 v212, v212
	v_rcp_f32_e32 v213, v213
	v_rcp_f32_e32 v214, v214
	v_rcp_f32_e32 v215, v215
	v_rcp_f32_e32 v216, v216
	v_rcp_f32_e32 v217, v217
	v_pk_mul_f32 v[202:203], v[202:203], v[210:211]
	v_pk_mul_f32 v[204:205], v[204:205], v[212:213]
	v_pk_mul_f32 v[206:207], v[206:207], v[214:215]
	v_pk_mul_f32 v[208:209], v[208:209], v[216:217]
	v_cvt_pk_bf16_f32 v222, v202, v203
	v_cvt_pk_bf16_f32 v223, v204, v205
	v_cvt_pk_bf16_f32 v224, v206, v207
	v_cvt_pk_bf16_f32 v225, v208, v209
	global_store_dwordx4 v239, v[222:225], s[24:25] offset:3072 sc0 sc1
	s_add_u32 s5, s5, 1
	s_cmp_lt_u32 s5, s6
	s_cbranch_scc1 .Lssdp_unit
	s_waitcnt vmcnt(0)
	s_barrier
	s_cmp_lg_u32 s82, 0
	s_cbranch_scc1 .Lssdp_wait_done
	s_mov_b64 exec, 1
	s_lshl_b32 s20, s0, 1
	s_add_u32 s20, s20, s4
	s_lshl_b32 s20, s20, 6
	s_add_u32 s20, s20, 0x1241d000
	s_add_u32 s58, s50, s20
	s_addc_u32 s59, s51, 0
	v_mov_b32_e32 v230, 0
	v_mov_b32_e32 v231, 1
	global_atomic_add v230, v231, s[58:59]
	s_waitcnt vmcnt(0)
	s_mov_b32 s60, 0
